# attention: first-fragment exps issued speculatively inside the row-max chain (recomputed on the rare rescale path), on top of hand-scheduled S2
# baseline (speedup 1.0000x reference)
; DI float ex2(float x) { return __builtin_amdgcn_exp2f(x); }
; DI float swap_max(float m) { auto rr = __builtin_amdgcn_permlane32_swap(__float_as_uint(m), __float_as_uint(m), false, false); return __builtin_fmaxf(__uint_as_float(rr[0]), __uint_as_float(rr[1])); }
; #define GLOAD(t_, slotoff_) do { const char* kb_ = KGc + ((size_t)(t_) << 14); const char* vb_ = VGc + ((size_t)(t_) << 14); \
;         const unsigned d_ = (unsigned)__builtin_amdgcn_readfirstlane((int)(ldsbase + (slotoff_) + wid * 1024)); \
;         GLDS16(kb_, d_); GLDS16(kb_ + 8192, d_ + 8192u); GLDS16(vb_, d_ + 16384u); GLDS16(vb_ + 8192, d_ + 24576u); } while (0)
; #define MX3(a_, b_, c_) __builtin_fmaxf(__builtin_fmaxf((a_), (b_)), (c_))
; #define EXPQ(S, lo_, RS, PF) do { _Pragma("unroll") for (int i = lo_; i < lo_ + 8; ++i) { S[i] = ex2(S[i]); RS += S[i]; } \
;               u32x4 w_; w_.x = pk2(S[lo_], S[lo_ + 1]); w_.y = pk2(S[lo_ + 2], S[lo_ + 3]); w_.z = pk2(S[lo_ + 4], S[lo_ + 5]); w_.w = pk2(S[lo_ + 6], S[lo_ + 7]); PF = __builtin_bit_cast(bf16x8, w_); } while (0)
; DI void attn_unit(const Params& p, int bh, int qb, char* lds, float lam, int tid, int lane, int wid, const bool build_tab) {
;     ...
;             float mxa = MX3(s0[0], s0[1], s1[0]), mxb = MX3(s0[2], s0[3], s1[1]); mxa = MX3(mxa, s1[2], s1[3]);
; #pragma unroll
;             for (int r = 4; r < 16; r += 4) { mxa = MX3(mxa, s0[r], s0[r + 1]); mxb = MX3(mxb, s0[r + 2], s0[r + 3]); mxa = MX3(mxa, s1[r], s1[r + 1]); mxb = MX3(mxb, s1[r + 2], s1[r + 3]); }
;             float mx = swap_max(__builtin_fmaxf(mxa, mxb));
;             const bool first = (t == 0);
;             if (first || __builtin_amdgcn_ballot_w64(mx > 8.0f) != 0ull) {
;                 const float dl = first ? mx : __builtin_fmaxf(mx, 0.f);
;                 const float f = first ? 1.0f : ex2(-dl);
;                 l *= f; nm -= dl;
; #pragma unroll
;                 for (int i = 0; i < 16; ++i) { o[0][i] *= f; o[1][i] *= f; o[2][i] *= f; o[3][i] *= f; cinit[i] = nm; s0[i] -= dl; s1[i] -= dl; }
;             }
;             asm volatile("s_waitcnt vmcnt(0)" ::: "memory");
;             if (t + 2 < NT) GLOAD(t + 2, sn2);
;             float rs0 = 0.f, rs1 = 0.f;
;     ...
;             EXPQ(s0, 0, rs0, pf[0]);
.LBB0_355:
	s_nop 1
	v_max_f32_e32 v221, v96, v97
	s_nop 7
	v_max3_f32 v253, v98, v99, v81
	v_exp_f32_e32 v222, v96
	v_max3_f32 v221, v221, v80, v82
	v_max3_f32 v221, v221, v83, v100
	v_exp_f32_e32 v224, v97
	v_max3_f32 v253, v253, v102, v103
	v_max3_f32 v221, v221, v101, v84
	v_exp_f32_e32 v226, v98
	v_max3_f32 v253, v253, v86, v87
	v_max3_f32 v221, v221, v85, v104
	v_exp_f32_e32 v228, v99
	v_max3_f32 v253, v253, v106, v107
	v_max3_f32 v221, v221, v105, v88
	v_exp_f32_e32 v230, v100
	v_max3_f32 v253, v253, v90, v91
	v_max3_f32 v221, v221, v89, v108
	v_exp_f32_e32 v232, v101
	v_max3_f32 v253, v253, v110, v111
	v_max3_f32 v221, v221, v109, v92
	v_exp_f32_e32 v234, v102
	v_max3_f32 v253, v253, v94, v95
	v_max3_f32 v221, v221, v93, v253
	v_exp_f32_e32 v236, v103
	v_mov_b32_e32 v253, v221
	s_nop 1
	v_permlane32_swap_b32_e32 v221, v253
	v_max_f32_e32 v221, v221, v253
	v_cmp_lt_f32_e32 vcc, s41, v221
	s_cbranch_vccz .LBB0_357
	v_max_f32_e32 v65, v221, v221
	v_max_f32_e32 v65, 0, v65
	v_exp_f32_e64 v66, -v65
	v_sub_f32_e32 v64, v64, v65
	v_sub_f32_e32 v111, v111, v65
	v_sub_f32_e32 v110, v110, v65
	v_pk_mul_f32 v[62:63], v[62:63], v[66:67] op_sel_hi:[1,0]
	v_pk_mul_f32 v[60:61], v[60:61], v[66:67] op_sel_hi:[1,0]
	v_pk_mul_f32 v[58:59], v[58:59], v[66:67] op_sel_hi:[1,0]
	v_pk_mul_f32 v[56:57], v[56:57], v[66:67] op_sel_hi:[1,0]
	v_pk_mul_f32 v[54:55], v[54:55], v[66:67] op_sel_hi:[1,0]
	v_pk_mul_f32 v[52:53], v[52:53], v[66:67] op_sel_hi:[1,0]
	v_pk_mul_f32 v[50:51], v[50:51], v[66:67] op_sel_hi:[1,0]
	v_pk_mul_f32 v[48:49], v[48:49], v[66:67] op_sel_hi:[1,0]
	v_pk_mul_f32 v[46:47], v[46:47], v[66:67] op_sel_hi:[1,0]
	v_pk_mul_f32 v[44:45], v[44:45], v[66:67] op_sel_hi:[1,0]
	v_pk_mul_f32 v[42:43], v[42:43], v[66:67] op_sel_hi:[1,0]
	v_pk_mul_f32 v[40:41], v[40:41], v[66:67] op_sel_hi:[1,0]
	v_pk_mul_f32 v[38:39], v[38:39], v[66:67] op_sel_hi:[1,0]
	v_pk_mul_f32 v[36:37], v[36:37], v[66:67] op_sel_hi:[1,0]
	v_pk_mul_f32 v[34:35], v[34:35], v[66:67] op_sel_hi:[1,0]
	v_pk_mul_f32 v[32:33], v[32:33], v[66:67] op_sel_hi:[1,0]
	v_pk_mul_f32 v[30:31], v[30:31], v[66:67] op_sel_hi:[1,0]
	v_pk_mul_f32 v[28:29], v[28:29], v[66:67] op_sel_hi:[1,0]
	v_pk_mul_f32 v[26:27], v[26:27], v[66:67] op_sel_hi:[1,0]
	v_pk_mul_f32 v[24:25], v[24:25], v[66:67] op_sel_hi:[1,0]
	v_pk_mul_f32 v[22:23], v[22:23], v[66:67] op_sel_hi:[1,0]
	v_pk_mul_f32 v[20:21], v[20:21], v[66:67] op_sel_hi:[1,0]
	v_pk_mul_f32 v[18:19], v[18:19], v[66:67] op_sel_hi:[1,0]
	v_pk_mul_f32 v[16:17], v[16:17], v[66:67] op_sel_hi:[1,0]
	v_pk_mul_f32 v[14:15], v[14:15], v[66:67] op_sel_hi:[1,0]
	v_pk_mul_f32 v[12:13], v[12:13], v[66:67] op_sel_hi:[1,0]
	v_pk_mul_f32 v[10:11], v[10:11], v[66:67] op_sel_hi:[1,0]
	v_pk_mul_f32 v[8:9], v[8:9], v[66:67] op_sel_hi:[1,0]
	v_pk_mul_f32 v[6:7], v[6:7], v[66:67] op_sel_hi:[1,0]
	v_pk_mul_f32 v[4:5], v[4:5], v[66:67] op_sel_hi:[1,0]
	v_pk_mul_f32 v[2:3], v[2:3], v[66:67] op_sel_hi:[1,0]
	v_pk_mul_f32 v[0:1], v[0:1], v[66:67] op_sel_hi:[1,0]
	v_sub_f32_e32 v109, v109, v65
	v_sub_f32_e32 v108, v108, v65
	v_sub_f32_e32 v107, v107, v65
	v_sub_f32_e32 v106, v106, v65
	v_sub_f32_e32 v105, v105, v65
	v_sub_f32_e32 v104, v104, v65
	v_sub_f32_e32 v103, v103, v65
	v_sub_f32_e32 v102, v102, v65
	v_sub_f32_e32 v101, v101, v65
	v_sub_f32_e32 v100, v100, v65
	v_sub_f32_e32 v99, v99, v65
	v_sub_f32_e32 v98, v98, v65
	v_sub_f32_e32 v97, v97, v65
	v_sub_f32_e32 v96, v96, v65
	v_sub_f32_e32 v95, v95, v65
	v_sub_f32_e32 v94, v94, v65
	v_sub_f32_e32 v93, v93, v65
	v_sub_f32_e32 v92, v92, v65
	v_sub_f32_e32 v91, v91, v65
	v_sub_f32_e32 v90, v90, v65
	v_sub_f32_e32 v89, v89, v65
	v_sub_f32_e32 v88, v88, v65
	v_sub_f32_e32 v87, v87, v65
	v_sub_f32_e32 v86, v86, v65
	v_sub_f32_e32 v85, v85, v65
	v_sub_f32_e32 v84, v84, v65
	v_sub_f32_e32 v83, v83, v65
	v_sub_f32_e32 v82, v82, v65
	v_sub_f32_e32 v81, v81, v65
	v_sub_f32_e32 v80, v80, v65
	v_mul_f32_e32 v146, v146, v66
	v_mov_b32_e32 v65, v64
	v_mov_b32_e32 v66, v64
	v_mov_b32_e32 v67, v64
	v_mov_b32_e32 v68, v64
	v_mov_b32_e32 v69, v64
	v_mov_b32_e32 v70, v64
	v_mov_b32_e32 v71, v64
	v_mov_b32_e32 v72, v64
	v_mov_b32_e32 v73, v64
	v_mov_b32_e32 v74, v64
	v_mov_b32_e32 v75, v64
	v_mov_b32_e32 v76, v64
	v_mov_b32_e32 v77, v64
	v_mov_b32_e32 v78, v64
	v_mov_b32_e32 v79, v64
	v_exp_f32_e32 v222, v96
	v_exp_f32_e32 v224, v97
	v_exp_f32_e32 v226, v98
	v_exp_f32_e32 v228, v99
	v_exp_f32_e32 v230, v100
	v_exp_f32_e32 v232, v101
	v_exp_f32_e32 v234, v102
	v_exp_f32_e32 v236, v103

; #define LOADV(dst, ks_) do { _Pragma("unroll") for (int dvb = 0; dvb < 4; ++dvb) { dst[2 * dvb] = vtr(vp + dvb * 4096 + (ks_) * 1024); dst[2 * dvb + 1] = vtr(vp + dvb * 4096 + (ks_) * 1024 + 512); } } while (0)
; #define MF4(src, pfrag) do { _Pragma("unroll") for (int dvb = 0; dvb < 4; ++dvb) { \
;         const bf16x8 vf_ = __builtin_shufflevector(src[2 * dvb], src[2 * dvb + 1], 0, 1, 2, 3, 4, 5, 6, 7); o[dvb] = MFMA32(vf_, pfrag, o[dvb]); } } while (0)
; #define EXPQ(S, lo_, RS, PF) do { _Pragma("unroll") for (int i = lo_; i < lo_ + 8; ++i) { S[i] = ex2(S[i]); RS += S[i]; } \
;               u32x4 w_; w_.x = pk2(S[lo_], S[lo_ + 1]); w_.y = pk2(S[lo_ + 2], S[lo_ + 3]); w_.z = pk2(S[lo_ + 4], S[lo_ + 5]); w_.w = pk2(S[lo_ + 6], S[lo_ + 7]); PF = __builtin_bit_cast(bf16x8, w_); } while (0)
; DI void attn_unit(const Params& p, int bh, int qb, char* lds, float lam, int tid, int lane, int wid, const bool build_tab) {
;     ...
;             EXPQ(s0, 0, rs0, pf[0]);
;             LOADV(vb, 1);
;             MF4(va, pf[0]);
;             EXPQ(s0, 8, rs1, pf[1]);
;             LOADV(va, 2);
;             MF4(vb, pf[1]);
;             EXPQ(s1, 0, rs0, pf[2]);
;             LOADV(vb, 3);
;             MF4(va, pf[2]);
;             EXPQ(s1, 8, rs1, pf[3]);
;             MF4(vb, pf[3]);
;             l += rs0 + rs1;
.LBB0_359:
	ds_read_b64_tr_b16 v[242:243], v220 offset:21504
	ds_read_b64_tr_b16 v[244:245], v220 offset:22016
	ds_read_b64_tr_b16 v[246:247], v220 offset:25600
	ds_read_b64_tr_b16 v[248:249], v220 offset:26112
	v_cvt_pk_bf16_f32 v96, v222, v224
	v_cvt_pk_bf16_f32 v97, v226, v228
	v_cvt_pk_bf16_f32 v98, v230, v232
	v_cvt_pk_bf16_f32 v99, v234, v236
	ds_read_b64_tr_b16 v[100:101], v220 offset:17408
	ds_read_b64_tr_b16 v[102:103], v220 offset:17920
	s_waitcnt lgkmcnt(12)
	v_mfma_f32_32x32x16_bf16 v[48:63], v[140:143], v[96:99], v[48:63]
	ds_read_b64_tr_b16 v[250:251], v220 offset:29696
	ds_read_b64_tr_b16 v[252:253], v220 offset:30208
	v_exp_f32_e32 v223, v104
	v_exp_f32_e32 v225, v105
	v_exp_f32_e32 v227, v106
	v_add_f32_e32 v221, v224, v222
	s_waitcnt lgkmcnt(12)
	v_mfma_f32_32x32x16_bf16 v[32:47], v[136:139], v[96:99], v[32:47]
	v_exp_f32_e32 v229, v107
	v_exp_f32_e32 v231, v108
	v_exp_f32_e32 v233, v109
	v_add_f32_e32 v221, v226, v221
	s_waitcnt lgkmcnt(10)
	v_mfma_f32_32x32x16_bf16 v[16:31], v[132:135], v[96:99], v[16:31]
	v_exp_f32_e32 v235, v110
	v_exp_f32_e32 v237, v111
	v_add_f32_e32 v221, v228, v221
	v_add_f32_e32 v221, v230, v221
	ds_read_b64_tr_b16 v[104:105], v220 offset:18432
	ds_read_b64_tr_b16 v[106:107], v220 offset:18944
	ds_read_b64_tr_b16 v[108:109], v220 offset:19456
	ds_read_b64_tr_b16 v[110:111], v220 offset:19968
	s_waitcnt lgkmcnt(12)
	v_mfma_f32_32x32x16_bf16 v[0:15], v[128:131], v[96:99], v[0:15]
	ds_read_b64_tr_b16 v[128:129], v220 offset:26624
	ds_read_b64_tr_b16 v[130:131], v220 offset:27136
	v_cvt_pk_bf16_f32 v96, v223, v225
	v_cvt_pk_bf16_f32 v97, v227, v229
	v_cvt_pk_bf16_f32 v98, v231, v233
	v_cvt_pk_bf16_f32 v99, v235, v237
	v_exp_f32_e32 v140, v84
	v_exp_f32_e32 v142, v85
	s_waitcnt lgkmcnt(8)
	v_mfma_f32_32x32x16_bf16 v[48:63], v[100:103], v[96:99], v[48:63]
	v_exp_f32_e32 v238, v86
	v_exp_f32_e32 v240, v87
	v_add_f32_e32 v221, v232, v221
	ds_read_b64_tr_b16 v[84:85], v220 offset:22528
	ds_read_b64_tr_b16 v[86:87], v220 offset:23040
	v_exp_f32_e32 v136, v82
	s_waitcnt lgkmcnt(14)
	v_mfma_f32_32x32x16_bf16 v[32:47], v[242:245], v[96:99], v[32:47]
	ds_read_b64_tr_b16 v[242:243], v220 offset:23552
	ds_read_b64_tr_b16 v[244:245], v220 offset:24064
	v_exp_f32_e32 v138, v83
	v_exp_f32_e32 v132, v80
	v_exp_f32_e32 v134, v81
	v_add_f32_e32 v221, v234, v221
	s_waitcnt lgkmcnt(14)
	v_mfma_f32_32x32x16_bf16 v[16:31], v[246:249], v[96:99], v[16:31]
	ds_read_b64_tr_b16 v[246:247], v220 offset:27648
	ds_read_b64_tr_b16 v[248:249], v220 offset:28160
	v_cvt_pk_bf16_f32 v80, v132, v134
	v_cvt_pk_bf16_f32 v81, v136, v138
	v_cvt_pk_bf16_f32 v82, v140, v142
	v_cvt_pk_bf16_f32 v83, v238, v240
	v_exp_f32_e32 v133, v88
	v_exp_f32_e32 v135, v89
	s_waitcnt lgkmcnt(12)
	v_mfma_f32_32x32x16_bf16 v[0:15], v[250:253], v[96:99], v[0:15]
	ds_read_b64_tr_b16 v[250:251], v220 offset:31744
	ds_read_b64_tr_b16 v[252:253], v220 offset:32256
	v_exp_f32_e32 v137, v90
	v_exp_f32_e32 v139, v91
	v_add_f32_e32 v221, v236, v221
	ds_read_b64_tr_b16 v[88:89], v220 offset:30720
	ds_read_b64_tr_b16 v[90:91], v220 offset:31232
	v_exp_f32_e32 v141, v92
	s_waitcnt lgkmcnt(14)
	v_mfma_f32_32x32x16_bf16 v[48:63], v[104:107], v[80:83], v[48:63]
	v_exp_f32_e32 v143, v93
	v_exp_f32_e32 v239, v94
	v_exp_f32_e32 v241, v95
	v_add_f32_e32 v221, v132, v221
	s_waitcnt lgkmcnt(8)
	v_mfma_f32_32x32x16_bf16 v[32:47], v[84:87], v[80:83], v[32:47]
	v_add_f32_e32 v93, v225, v223
	v_add_f32_e32 v221, v134, v221
	v_add_f32_e32 v93, v227, v93
	v_add_f32_e32 v221, v136, v221
	v_add_f32_e32 v93, v229, v93
	v_add_f32_e32 v221, v138, v221
	s_waitcnt lgkmcnt(10)
	v_mfma_f32_32x32x16_bf16 v[16:31], v[128:131], v[80:83], v[16:31]
	v_add_f32_e32 v93, v231, v93
	v_add_f32_e32 v221, v140, v221
	v_add_f32_e32 v93, v233, v93
	v_add_f32_e32 v221, v142, v221
	v_add_f32_e32 v93, v235, v93
	v_add_f32_e32 v221, v238, v221
	v_add_f32_e32 v93, v237, v93
	s_waitcnt lgkmcnt(0)
	v_mfma_f32_32x32x16_bf16 v[0:15], v[88:91], v[80:83], v[0:15]
	v_cvt_pk_bf16_f32 v80, v133, v135
	v_cvt_pk_bf16_f32 v81, v137, v139
	v_cvt_pk_bf16_f32 v82, v141, v143
	v_cvt_pk_bf16_f32 v83, v239, v241
	v_add_f32_e32 v221, v240, v221
	v_add_f32_e32 v93, v133, v93
	s_waitcnt lgkmcnt(12)
	v_mfma_f32_32x32x16_bf16 v[48:63], v[108:111], v[80:83], v[48:63]
	v_add_f32_e32 v93, v135, v93
	v_add_f32_e32 v93, v137, v93
	s_waitcnt lgkmcnt(6)
	v_mfma_f32_32x32x16_bf16 v[32:47], v[242:245], v[80:83], v[32:47]
	v_add_f32_e32 v93, v139, v93
	v_add_f32_e32 v93, v141, v93
	s_waitcnt lgkmcnt(4)
	v_mfma_f32_32x32x16_bf16 v[16:31], v[246:249], v[80:83], v[16:31]
	v_add_f32_e32 v93, v143, v93
	v_add_f32_e32 v93, v239, v93
	s_waitcnt lgkmcnt(2)
	v_mfma_f32_32x32x16_bf16 v[0:15], v[250:253], v[80:83], v[0:15]
	v_add_f32_e32 v93, v241, v93
	v_add_f32_e32 v221, v221, v93
	v_add_f32_e32 v146, v146, v221

; DI float ex2(float x) { return __builtin_amdgcn_exp2f(x); }
; DI float swap_max(float m) { auto rr = __builtin_amdgcn_permlane32_swap(__float_as_uint(m), __float_as_uint(m), false, false); return __builtin_fmaxf(__uint_as_float(rr[0]), __uint_as_float(rr[1])); }
; #define GLOAD(t_, slotoff_) do { const char* kb_ = KGc + ((size_t)(t_) << 14); const char* vb_ = VGc + ((size_t)(t_) << 14); \
;         const unsigned d_ = (unsigned)__builtin_amdgcn_readfirstlane((int)(ldsbase + (slotoff_) + wid * 1024)); \
;         GLDS16(kb_, d_); GLDS16(kb_ + 8192, d_ + 8192u); GLDS16(vb_, d_ + 16384u); GLDS16(vb_ + 8192, d_ + 24576u); } while (0)
; #define MX3(a_, b_, c_) __builtin_fmaxf(__builtin_fmaxf((a_), (b_)), (c_))
; #define EXPQ(S, lo_, RS, PF) do { _Pragma("unroll") for (int i = lo_; i < lo_ + 8; ++i) { S[i] = ex2(S[i]); RS += S[i]; } \
;               u32x4 w_; w_.x = pk2(S[lo_], S[lo_ + 1]); w_.y = pk2(S[lo_ + 2], S[lo_ + 3]); w_.z = pk2(S[lo_ + 4], S[lo_ + 5]); w_.w = pk2(S[lo_ + 6], S[lo_ + 7]); PF = __builtin_bit_cast(bf16x8, w_); } while (0)
; DI void attn_unit(const Params& p, int bh, int qb, char* lds, float lam, int tid, int lane, int wid, const bool build_tab) {
;     ...
;             float mxa = MX3(s0[0], s0[1], s1[0]), mxb = MX3(s0[2], s0[3], s1[1]); mxa = MX3(mxa, s1[2], s1[3]);
; #pragma unroll
;             for (int r = 4; r < 16; r += 4) { mxa = MX3(mxa, s0[r], s0[r + 1]); mxb = MX3(mxb, s0[r + 2], s0[r + 3]); mxa = MX3(mxa, s1[r], s1[r + 1]); mxb = MX3(mxb, s1[r + 2], s1[r + 3]); }
;             float mx = swap_max(__builtin_fmaxf(mxa, mxb));
;             const bool first = (t == 0);
;             if (first || __builtin_amdgcn_ballot_w64(mx > 8.0f) != 0ull) {
;                 const float dl = first ? mx : __builtin_fmaxf(mx, 0.f);
;                 const float f = first ? 1.0f : ex2(-dl);
;                 l *= f; nm -= dl;
; #pragma unroll
;                 for (int i = 0; i < 16; ++i) { o[0][i] *= f; o[1][i] *= f; o[2][i] *= f; o[3][i] *= f; cinit[i] = nm; s0[i] -= dl; s1[i] -= dl; }
;             }
;             asm volatile("s_waitcnt vmcnt(0)" ::: "memory");
;             if (t + 2 < NT) GLOAD(t + 2, sn2);
;             float rs0 = 0.f, rs1 = 0.f;
;     ...
;             EXPQ(s0, 0, rs0, pf[0]);
.LBB0_375:
	s_nop 1
	v_max_f32_e32 v242, v96, v97
	s_nop 7
	v_max3_f32 v243, v98, v99, v81
	v_exp_f32_e32 v178, v96
	v_max3_f32 v242, v242, v80, v82
	v_max3_f32 v242, v242, v83, v100
	v_exp_f32_e32 v180, v97
	v_max3_f32 v243, v243, v102, v103
	v_max3_f32 v242, v242, v101, v84
	v_exp_f32_e32 v182, v98
	v_max3_f32 v243, v243, v86, v87
	v_max3_f32 v242, v242, v85, v104
	v_exp_f32_e32 v184, v99
	v_max3_f32 v243, v243, v106, v107
	v_max3_f32 v242, v242, v105, v88
	v_exp_f32_e32 v186, v100
	v_max3_f32 v243, v243, v90, v91
	v_max3_f32 v242, v242, v89, v108
	v_exp_f32_e32 v188, v101
	v_max3_f32 v243, v243, v110, v111
	v_max3_f32 v242, v242, v109, v92
	v_exp_f32_e32 v190, v102
	v_max3_f32 v243, v243, v94, v95
	v_max3_f32 v242, v242, v93, v243
	v_exp_f32_e32 v192, v103
	v_mov_b32_e32 v243, v242
	s_nop 1
	v_permlane32_swap_b32_e32 v242, v243
	v_max_f32_e32 v242, v242, v243
	v_cmp_lt_f32_e32 vcc, s41, v242
	s_cbranch_vccz .LBB0_377
	v_max_f32_e32 v65, v242, v242
	v_max_f32_e32 v65, 0, v65
	v_exp_f32_e64 v66, -v65
	v_sub_f32_e32 v64, v64, v65
	v_sub_f32_e32 v111, v111, v65
	v_sub_f32_e32 v110, v110, v65
	v_pk_mul_f32 v[62:63], v[62:63], v[66:67] op_sel_hi:[1,0]
	v_pk_mul_f32 v[60:61], v[60:61], v[66:67] op_sel_hi:[1,0]
	v_pk_mul_f32 v[58:59], v[58:59], v[66:67] op_sel_hi:[1,0]
	v_pk_mul_f32 v[56:57], v[56:57], v[66:67] op_sel_hi:[1,0]
	v_pk_mul_f32 v[54:55], v[54:55], v[66:67] op_sel_hi:[1,0]
	v_pk_mul_f32 v[52:53], v[52:53], v[66:67] op_sel_hi:[1,0]
	v_pk_mul_f32 v[50:51], v[50:51], v[66:67] op_sel_hi:[1,0]
	v_pk_mul_f32 v[48:49], v[48:49], v[66:67] op_sel_hi:[1,0]
	v_pk_mul_f32 v[46:47], v[46:47], v[66:67] op_sel_hi:[1,0]
	v_pk_mul_f32 v[44:45], v[44:45], v[66:67] op_sel_hi:[1,0]
	v_pk_mul_f32 v[42:43], v[42:43], v[66:67] op_sel_hi:[1,0]
	v_pk_mul_f32 v[40:41], v[40:41], v[66:67] op_sel_hi:[1,0]
	v_pk_mul_f32 v[38:39], v[38:39], v[66:67] op_sel_hi:[1,0]
	v_pk_mul_f32 v[36:37], v[36:37], v[66:67] op_sel_hi:[1,0]
	v_pk_mul_f32 v[34:35], v[34:35], v[66:67] op_sel_hi:[1,0]
	v_pk_mul_f32 v[32:33], v[32:33], v[66:67] op_sel_hi:[1,0]
	v_pk_mul_f32 v[30:31], v[30:31], v[66:67] op_sel_hi:[1,0]
	v_pk_mul_f32 v[28:29], v[28:29], v[66:67] op_sel_hi:[1,0]
	v_pk_mul_f32 v[26:27], v[26:27], v[66:67] op_sel_hi:[1,0]
	v_pk_mul_f32 v[24:25], v[24:25], v[66:67] op_sel_hi:[1,0]
	v_pk_mul_f32 v[22:23], v[22:23], v[66:67] op_sel_hi:[1,0]
	v_pk_mul_f32 v[20:21], v[20:21], v[66:67] op_sel_hi:[1,0]
	v_pk_mul_f32 v[18:19], v[18:19], v[66:67] op_sel_hi:[1,0]
	v_pk_mul_f32 v[16:17], v[16:17], v[66:67] op_sel_hi:[1,0]
	v_pk_mul_f32 v[14:15], v[14:15], v[66:67] op_sel_hi:[1,0]
	v_pk_mul_f32 v[12:13], v[12:13], v[66:67] op_sel_hi:[1,0]
	v_pk_mul_f32 v[10:11], v[10:11], v[66:67] op_sel_hi:[1,0]
	v_pk_mul_f32 v[8:9], v[8:9], v[66:67] op_sel_hi:[1,0]
	v_pk_mul_f32 v[6:7], v[6:7], v[66:67] op_sel_hi:[1,0]
	v_pk_mul_f32 v[4:5], v[4:5], v[66:67] op_sel_hi:[1,0]
	v_pk_mul_f32 v[2:3], v[2:3], v[66:67] op_sel_hi:[1,0]
	v_pk_mul_f32 v[0:1], v[0:1], v[66:67] op_sel_hi:[1,0]
	v_sub_f32_e32 v109, v109, v65
	v_sub_f32_e32 v108, v108, v65
	v_sub_f32_e32 v107, v107, v65
	v_sub_f32_e32 v106, v106, v65
	v_sub_f32_e32 v105, v105, v65
	v_sub_f32_e32 v104, v104, v65
	v_sub_f32_e32 v103, v103, v65
	v_sub_f32_e32 v102, v102, v65
	v_sub_f32_e32 v101, v101, v65
	v_sub_f32_e32 v100, v100, v65
	v_sub_f32_e32 v99, v99, v65
	v_sub_f32_e32 v98, v98, v65
	v_sub_f32_e32 v97, v97, v65
	v_sub_f32_e32 v96, v96, v65
	v_sub_f32_e32 v95, v95, v65
	v_sub_f32_e32 v94, v94, v65
	v_sub_f32_e32 v93, v93, v65
	v_sub_f32_e32 v92, v92, v65
	v_sub_f32_e32 v91, v91, v65
	v_sub_f32_e32 v90, v90, v65
	v_sub_f32_e32 v89, v89, v65
	v_sub_f32_e32 v88, v88, v65
	v_sub_f32_e32 v87, v87, v65
	v_sub_f32_e32 v86, v86, v65
	v_sub_f32_e32 v85, v85, v65
	v_sub_f32_e32 v84, v84, v65
	v_sub_f32_e32 v83, v83, v65
	v_sub_f32_e32 v82, v82, v65
	v_sub_f32_e32 v81, v81, v65
	v_sub_f32_e32 v80, v80, v65
	v_mul_f32_e32 v176, v176, v66
	v_mov_b32_e32 v65, v64
	v_mov_b32_e32 v66, v64
	v_mov_b32_e32 v67, v64
	v_mov_b32_e32 v68, v64
	v_mov_b32_e32 v69, v64
	v_mov_b32_e32 v70, v64
	v_mov_b32_e32 v71, v64
	v_mov_b32_e32 v72, v64
	v_mov_b32_e32 v73, v64
	v_mov_b32_e32 v74, v64
	v_mov_b32_e32 v75, v64
	v_mov_b32_e32 v76, v64
	v_mov_b32_e32 v77, v64
	v_mov_b32_e32 v78, v64
	v_mov_b32_e32 v79, v64
	v_exp_f32_e32 v178, v96
	v_exp_f32_e32 v180, v97
	v_exp_f32_e32 v182, v98
	v_exp_f32_e32 v184, v99
	v_exp_f32_e32 v186, v100
	v_exp_f32_e32 v188, v101
	v_exp_f32_e32 v190, v102
	v_exp_f32_e32 v192, v103

; #define LOADV(dst, ks_) do { _Pragma("unroll") for (int dvb = 0; dvb < 4; ++dvb) { dst[2 * dvb] = vtr(vp + dvb * 4096 + (ks_) * 1024); dst[2 * dvb + 1] = vtr(vp + dvb * 4096 + (ks_) * 1024 + 512); } } while (0)
; #define MF4(src, pfrag) do { _Pragma("unroll") for (int dvb = 0; dvb < 4; ++dvb) { \
;         const bf16x8 vf_ = __builtin_shufflevector(src[2 * dvb], src[2 * dvb + 1], 0, 1, 2, 3, 4, 5, 6, 7); o[dvb] = MFMA32(vf_, pfrag, o[dvb]); } } while (0)
; #define EXPQ(S, lo_, RS, PF) do { _Pragma("unroll") for (int i = lo_; i < lo_ + 8; ++i) { S[i] = ex2(S[i]); RS += S[i]; } \
;               u32x4 w_; w_.x = pk2(S[lo_], S[lo_ + 1]); w_.y = pk2(S[lo_ + 2], S[lo_ + 3]); w_.z = pk2(S[lo_ + 4], S[lo_ + 5]); w_.w = pk2(S[lo_ + 6], S[lo_ + 7]); PF = __builtin_bit_cast(bf16x8, w_); } while (0)
; DI void attn_unit(const Params& p, int bh, int qb, char* lds, float lam, int tid, int lane, int wid, const bool build_tab) {
;     ...
;             EXPQ(s0, 0, rs0, pf[0]);
;             LOADV(vb, 1);
;             MF4(va, pf[0]);
;             EXPQ(s0, 8, rs1, pf[1]);
;             LOADV(va, 2);
;             MF4(vb, pf[1]);
;             EXPQ(s1, 0, rs0, pf[2]);
;             LOADV(vb, 3);
;             MF4(va, pf[2]);
;             EXPQ(s1, 8, rs1, pf[3]);
;             MF4(vb, pf[3]);
;             l += rs0 + rs1;
.LBB0_379:
	ds_read_b64_tr_b16 v[230:231], v177 offset:21504
	ds_read_b64_tr_b16 v[232:233], v177 offset:22016
	ds_read_b64_tr_b16 v[234:235], v177 offset:25600
	ds_read_b64_tr_b16 v[236:237], v177 offset:26112
	v_cvt_pk_bf16_f32 v96, v178, v180
	v_cvt_pk_bf16_f32 v97, v182, v184
	v_cvt_pk_bf16_f32 v98, v186, v188
	v_cvt_pk_bf16_f32 v99, v190, v192
	ds_read_b64_tr_b16 v[100:101], v177 offset:17408
	ds_read_b64_tr_b16 v[102:103], v177 offset:17920
	s_waitcnt lgkmcnt(12)
	v_mfma_f32_32x32x16_bf16 v[48:63], v[140:143], v[96:99], v[48:63]
	ds_read_b64_tr_b16 v[238:239], v177 offset:29696
	ds_read_b64_tr_b16 v[240:241], v177 offset:30208
	v_exp_f32_e32 v179, v104
	v_exp_f32_e32 v181, v105
	v_exp_f32_e32 v183, v106
	v_add_f32_e32 v242, v180, v178
	s_waitcnt lgkmcnt(12)
	v_mfma_f32_32x32x16_bf16 v[32:47], v[136:139], v[96:99], v[32:47]
	v_exp_f32_e32 v185, v107
	v_exp_f32_e32 v187, v108
	v_exp_f32_e32 v189, v109
	v_add_f32_e32 v242, v182, v242
	s_waitcnt lgkmcnt(10)
	v_mfma_f32_32x32x16_bf16 v[16:31], v[132:135], v[96:99], v[16:31]
	v_exp_f32_e32 v191, v110
	v_exp_f32_e32 v193, v111
	v_add_f32_e32 v242, v184, v242
	v_add_f32_e32 v242, v186, v242
	ds_read_b64_tr_b16 v[104:105], v177 offset:18432
	ds_read_b64_tr_b16 v[106:107], v177 offset:18944
	ds_read_b64_tr_b16 v[108:109], v177 offset:19456
	ds_read_b64_tr_b16 v[110:111], v177 offset:19968
	s_waitcnt lgkmcnt(12)
	v_mfma_f32_32x32x16_bf16 v[0:15], v[128:131], v[96:99], v[0:15]
	ds_read_b64_tr_b16 v[128:129], v177 offset:26624
	ds_read_b64_tr_b16 v[130:131], v177 offset:27136
	v_cvt_pk_bf16_f32 v96, v179, v181
	v_cvt_pk_bf16_f32 v97, v183, v185
	v_cvt_pk_bf16_f32 v98, v187, v189
	v_cvt_pk_bf16_f32 v99, v191, v193
	v_exp_f32_e32 v140, v84
	v_exp_f32_e32 v142, v85
	s_waitcnt lgkmcnt(8)
	v_mfma_f32_32x32x16_bf16 v[48:63], v[100:103], v[96:99], v[48:63]
	v_exp_f32_e32 v194, v86
	v_exp_f32_e32 v196, v87
	v_add_f32_e32 v242, v188, v242
	ds_read_b64_tr_b16 v[84:85], v177 offset:22528
	ds_read_b64_tr_b16 v[86:87], v177 offset:23040
	v_exp_f32_e32 v136, v82
	s_waitcnt lgkmcnt(14)
	v_mfma_f32_32x32x16_bf16 v[32:47], v[230:233], v[96:99], v[32:47]
	ds_read_b64_tr_b16 v[230:231], v177 offset:23552
	ds_read_b64_tr_b16 v[232:233], v177 offset:24064
	v_exp_f32_e32 v138, v83
	v_exp_f32_e32 v132, v80
	v_exp_f32_e32 v134, v81
	v_add_f32_e32 v242, v190, v242
	s_waitcnt lgkmcnt(14)
	v_mfma_f32_32x32x16_bf16 v[16:31], v[234:237], v[96:99], v[16:31]
	ds_read_b64_tr_b16 v[234:235], v177 offset:27648
	ds_read_b64_tr_b16 v[236:237], v177 offset:28160
	v_cvt_pk_bf16_f32 v80, v132, v134
	v_cvt_pk_bf16_f32 v81, v136, v138
	v_cvt_pk_bf16_f32 v82, v140, v142
	v_cvt_pk_bf16_f32 v83, v194, v196
	v_exp_f32_e32 v133, v88
	v_exp_f32_e32 v135, v89
	s_waitcnt lgkmcnt(12)
	v_mfma_f32_32x32x16_bf16 v[0:15], v[238:241], v[96:99], v[0:15]
	ds_read_b64_tr_b16 v[238:239], v177 offset:31744
	ds_read_b64_tr_b16 v[240:241], v177 offset:32256
	v_exp_f32_e32 v137, v90
	v_exp_f32_e32 v139, v91
	v_add_f32_e32 v242, v192, v242
	ds_read_b64_tr_b16 v[88:89], v177 offset:30720
	ds_read_b64_tr_b16 v[90:91], v177 offset:31232
	v_exp_f32_e32 v141, v92
	s_waitcnt lgkmcnt(14)
	v_mfma_f32_32x32x16_bf16 v[48:63], v[104:107], v[80:83], v[48:63]
	v_exp_f32_e32 v143, v93
	v_exp_f32_e32 v195, v94
	v_exp_f32_e32 v197, v95
	v_add_f32_e32 v242, v132, v242
	s_waitcnt lgkmcnt(8)
	v_mfma_f32_32x32x16_bf16 v[32:47], v[84:87], v[80:83], v[32:47]
	v_add_f32_e32 v243, v181, v179
	v_add_f32_e32 v242, v134, v242
	v_add_f32_e32 v243, v183, v243
	v_add_f32_e32 v242, v136, v242
	v_add_f32_e32 v243, v185, v243
	v_add_f32_e32 v242, v138, v242
	s_waitcnt lgkmcnt(10)
	v_mfma_f32_32x32x16_bf16 v[16:31], v[128:131], v[80:83], v[16:31]
	v_add_f32_e32 v243, v187, v243
	v_add_f32_e32 v242, v140, v242
	v_add_f32_e32 v243, v189, v243
	v_add_f32_e32 v242, v142, v242
	v_add_f32_e32 v243, v191, v243
	v_add_f32_e32 v242, v194, v242
	v_add_f32_e32 v243, v193, v243
	s_waitcnt lgkmcnt(0)
	v_mfma_f32_32x32x16_bf16 v[0:15], v[88:91], v[80:83], v[0:15]
	v_cvt_pk_bf16_f32 v80, v133, v135
	v_cvt_pk_bf16_f32 v81, v137, v139
	v_cvt_pk_bf16_f32 v82, v141, v143
	v_cvt_pk_bf16_f32 v83, v195, v197
	v_add_f32_e32 v242, v196, v242
	v_add_f32_e32 v243, v133, v243
	s_waitcnt lgkmcnt(12)
	v_mfma_f32_32x32x16_bf16 v[48:63], v[108:111], v[80:83], v[48:63]
	v_add_f32_e32 v243, v135, v243
	v_add_f32_e32 v243, v137, v243
	s_waitcnt lgkmcnt(6)
	v_mfma_f32_32x32x16_bf16 v[32:47], v[230:233], v[80:83], v[32:47]
	v_add_f32_e32 v243, v139, v243
	v_add_f32_e32 v243, v141, v243
	s_waitcnt lgkmcnt(4)
	v_mfma_f32_32x32x16_bf16 v[16:31], v[234:237], v[80:83], v[16:31]
	v_add_f32_e32 v243, v143, v243
	v_add_f32_e32 v243, v195, v243
	s_waitcnt lgkmcnt(2)
	v_mfma_f32_32x32x16_bf16 v[0:15], v[238:241], v[80:83], v[0:15]
	v_add_f32_e32 v243, v197, v243
	v_add_f32_e32 v242, v242, v243
	v_add_f32_e32 v176, v176, v242
